# role A issues the next unit's first L slot after its epilogue instead of before (epilogue overlaps the other half's last MFMA slot)
# baseline (speedup 1.0000x reference)
; #define PG8_STAGE(bufoff, gbase, voff) do { _Pragma("unroll") for (int _i = 0; _i < 2; ++_i) \
;         __builtin_amdgcn_global_load_lds((const unsigned*)((const char*)(gbase) + (voff)[_i]), (PG8_LAS unsigned*)(lds + (bufoff) + ldsw + _i * 8192), 16, 0, 0); } while (0)
; #define PG8_LDA(dst, b, h) do { _Pragma("unroll") for (int m = 0; m < 4; ++m) _Pragma("unroll") for (int k = 0; k < 2; ++k) dst[m][k] = *(const PG8_LAS bf16x8*)(lds + PG8_SA(b, h) + aoff + m * 2048 + k * 1024); } while (0)
; #define PG8_LDB(dst, b, h) do { _Pragma("unroll") for (int n = 0; n < 2; ++n) _Pragma("unroll") for (int k = 0; k < 2; ++k) dst[n][k] = *(const PG8_LAS bf16x8*)(lds + PG8_SB(b, h) + boff + n * 2048 + k * 1024); } while (0)
; #define PG8_BAR __builtin_amdgcn_s_barrier()
; #define PG8_SCHED __builtin_amdgcn_sched_barrier(0)
; template <class Epi, class Sched, bool ALIGN_EPI>
; __device__ __forceinline__ void gemm_phase(PG8_LAS unsigned char* lds, const Gemm g, const Sched& S, const Epi& E) {
;     ...
;             const char* a2 = last ? nA : cA + (size_t)(t + 2) * kstepA; const char* b2 = last ? nB : cB + (size_t)(t + 2) * kstep;
;             const char* a3 = a2 + kstepA; const char* b3 = b2 + kstep;
;             PG8_LDB(B0, 0, 0); PG8_LDB(B1, 0, 1); PG8_SCHED; PG8_LDA(At, 0, 0); PG8_STAGE(PG8_SA(1, 1), a1 + hstepA, voffA);
;     ...
;         cur = nxt; cA = nA; cB = nB; ++ui;
;         if constexpr (ALIGN_EPI) { if (wr == 1) PG8_BAR; }
.LBB0_896:
	s_and_b64 vcc, exec, s[16:17]
	s_cbranch_vccz .Lhaft8_skip
	s_add_u32 s28, s24, 0x80
	s_addc_u32 s29, s25, 0
	ds_read_b128 v[190:193], v155 offset:0
	ds_read_b128 v[194:197], v155 offset:1024
	ds_read_b128 v[198:201], v155 offset:2048
	s_add_i32 m0, s2, 0x18000
	s_nop 0
	global_load_lds_dwordx4 v134, s[28:29]
	ds_read_b128 v[202:205], v155 offset:3072
	ds_read_b128 v[206:209], v155 offset:4096
	ds_read_b128 v[210:213], v155 offset:5120
	s_add_i32 m0, s2, 0x1a000
	s_nop 0
	global_load_lds_dwordx4 v130, s[28:29]
	ds_read_b128 v[214:217], v155 offset:6144
	ds_read_b128 v[218:221], v155 offset:7168
	ds_read_b128 v[156:159], v153 offset:0
	s_add_u32 s30, s28, 0x20000
	s_addc_u32 s31, s29, 0
	s_add_i32 m0, s2, 0x19000
	s_nop 0
	global_load_lds_dwordx4 v134, s[30:31]
	ds_read_b128 v[160:163], v153 offset:1024
	ds_read_b128 v[164:167], v153 offset:2048
	ds_read_b128 v[168:171], v153 offset:3072
	s_add_i32 m0, s2, 0x1b000
	s_nop 0
	global_load_lds_dwordx4 v130, s[30:31]
	ds_read_b128 v[174:177], v153 offset:16384
	ds_read_b128 v[178:181], v153 offset:17408
	ds_read_b128 v[182:185], v153 offset:18432
	s_add_u32 s30, s28, 0x80000
	s_addc_u32 s31, s29, 0
	s_add_i32 m0, s2, 0x1c000
	s_nop 0
	global_load_lds_dwordx4 v134, s[30:31]
	ds_read_b128 v[186:189], v153 offset:19456
	ds_read_b128 v[222:225], v155 offset:16384
	ds_read_b128 v[226:229], v155 offset:17408
	s_add_i32 m0, s2, 0x1e000
	s_nop 0
	global_load_lds_dwordx4 v130, s[30:31]
	ds_read_b128 v[230:233], v155 offset:18432
	ds_read_b128 v[234:237], v155 offset:19456
	ds_read_b128 v[238:241], v155 offset:20480
	s_add_u32 s30, s28, 0xa0000
	s_addc_u32 s31, s29, 0
	s_add_i32 m0, s2, 0x1d000
	s_nop 0
	global_load_lds_dwordx4 v134, s[30:31]
	ds_read_b128 v[242:245], v155 offset:21504
	ds_read_b128 v[246:249], v155 offset:22528
	ds_read_b128 v[250:253], v155 offset:23552
	s_add_i32 m0, s2, 0x1f000
	s_nop 0
	global_load_lds_dwordx4 v130, s[30:31]
	s_add_u32 s28, s28, 0x80
	s_addc_u32 s29, s29, 0

; #define PG8_STAGE(bufoff, gbase, voff) do { _Pragma("unroll") for (int _i = 0; _i < 2; ++_i) \
;         __builtin_amdgcn_global_load_lds((const unsigned*)((const char*)(gbase) + (voff)[_i]), (PG8_LAS unsigned*)(lds + (bufoff) + ldsw + _i * 8192), 16, 0, 0); } while (0)
; #define PG8_LDA(dst, b, h) do { _Pragma("unroll") for (int m = 0; m < 4; ++m) _Pragma("unroll") for (int k = 0; k < 2; ++k) dst[m][k] = *(const PG8_LAS bf16x8*)(lds + PG8_SA(b, h) + aoff + m * 2048 + k * 1024); } while (0)
; #define PG8_LDB(dst, b, h) do { _Pragma("unroll") for (int n = 0; n < 2; ++n) _Pragma("unroll") for (int k = 0; k < 2; ++k) dst[n][k] = *(const PG8_LAS bf16x8*)(lds + PG8_SB(b, h) + boff + n * 2048 + k * 1024); } while (0)
; #define PG8_SCHED __builtin_amdgcn_sched_barrier(0)
; template <class Epi, class Sched, bool ALIGN_EPI>
; __device__ __forceinline__ void gemm_phase(PG8_LAS unsigned char* lds, const Gemm g, const Sched& S, const Epi& E) {
;     ...
;         const size_t tail_ = has_next ? 0 : tailoff; const char* nA = (has_next ? (const char*)g.A + (size_t)nxt.pm * tstepA : cA) + (has_next ? 0 : tailoffA); const char* nB = (has_next ? (const char*)g.Bt + (size_t)nxt.pn * tstepB : cB) + tail_;
;         for (int t = 0; t < nt; t += 2) {
;             if constexpr (Epi::MIDK) { if (t == (nt >> 1)) E.midk(acc, cur, wr, fr); }
;             const bool last = (t == nt - 2);
;             const char* a1 = cA + (size_t)(t + 1) * kstepA;
;             const char* a2 = last ? nA : cA + (size_t)(t + 2) * kstepA; const char* b2 = last ? nB : cB + (size_t)(t + 2) * kstep;
;             const char* a3 = a2 + kstepA; const char* b3 = b2 + kstep;
;             PG8_LDB(B0, 0, 0); PG8_LDB(B1, 0, 1); PG8_SCHED; PG8_LDA(At, 0, 0); PG8_STAGE(PG8_SA(1, 1), a1 + hstepA, voffA);
.Lh8_join:
	s_add_u32 s28, s28, 0x80080
	s_addc_u32 s29, s29, 0
	s_and_b32 s2, s3, 0xfff
	s_mov_b32 s49, 0
	s_cmp_lt_u32 s3, 0x1000
	s_cbranch_scc0 .Lp8k_B_init
	s_setprio 0
	s_mov_b64 s[50:51], s[24:25]
	s_cmp_eq_u32 s42, 1
	s_cbranch_scc1 .Lp8k_A_first
	s_add_u32 s28, s30, 0x100
	s_addc_u32 s29, s31, 0
	s_branch .Lp8k_A_entry

; #define PG8_STAGE(bufoff, gbase, voff) do { _Pragma("unroll") for (int _i = 0; _i < 2; ++_i) \
;         __builtin_amdgcn_global_load_lds((const unsigned*)((const char*)(gbase) + (voff)[_i]), (PG8_LAS unsigned*)(lds + (bufoff) + ldsw + _i * 8192), 16, 0, 0); } while (0)
; #define PG8_LDA(dst, b, h) do { _Pragma("unroll") for (int m = 0; m < 4; ++m) _Pragma("unroll") for (int k = 0; k < 2; ++k) dst[m][k] = *(const PG8_LAS bf16x8*)(lds + PG8_SA(b, h) + aoff + m * 2048 + k * 1024); } while (0)
; #define PG8_LDB(dst, b, h) do { _Pragma("unroll") for (int n = 0; n < 2; ++n) _Pragma("unroll") for (int k = 0; k < 2; ++k) dst[n][k] = *(const PG8_LAS bf16x8*)(lds + PG8_SB(b, h) + boff + n * 2048 + k * 1024); } while (0)
; #define PG8_MMA(ai, bj, At, Bt) do { __builtin_amdgcn_s_setprio(1); _Pragma("unroll") for (int m = 0; m < 4; ++m) _Pragma("unroll") for (int n = 0; n < 2; ++n) _Pragma("unroll") for (int k = 0; k < 2; ++k) \
;         acc[ai][bj][m][n] = __builtin_amdgcn_mfma_f32_16x16x32_bf16(Bt[n][k], At[m][k], acc[ai][bj][m][n], 0, 0, 0); __builtin_amdgcn_s_setprio(0); } while (0)
; #define PG8_WAIT_V(n) asm volatile("s_waitcnt vmcnt(" #n ")" ::: "memory")
; #define PG8_WAIT_L(n) asm volatile("s_waitcnt lgkmcnt(" #n ")" ::: "memory")
; #define PG8_BAR __builtin_amdgcn_s_barrier()
; #define PG8_SCHED __builtin_amdgcn_sched_barrier(0)
; template <class Epi, class Sched, bool ALIGN_EPI>
; __device__ __forceinline__ void gemm_phase(PG8_LAS unsigned char* lds, const Gemm g, const Sched& S, const Epi& E) {
;     ...
;             PG8_LDB(B0, 0, 0); PG8_LDB(B1, 0, 1); PG8_SCHED; PG8_LDA(At, 0, 0); PG8_STAGE(PG8_SA(1, 1), a1 + hstepA, voffA);
;             PG8_WAIT_V(8); PG8_WAIT_L(0); PG8_BAR; PG8_MMA(0, 0, At, B0); PG8_MMA(0, 1, At, B1); PG8_BAR; PG8_SCHED;
;             PG8_LDA(At, 0, 1); PG8_STAGE(PG8_SB(0, 0), b2, voffB); PG8_STAGE(PG8_SB(0, 1), b2 + hstepB, voffB); PG8_STAGE(PG8_SA(0, 0), a2, voffA);
;             PG8_WAIT_V(8); PG8_WAIT_L(0); PG8_BAR; PG8_MMA(1, 0, At, B0); PG8_MMA(1, 1, At, B1); PG8_BAR; PG8_SCHED;
.Lp8k_A_loop:
	ds_read_b128 v[190:193], v155 offset:0
	ds_read_b128 v[194:197], v155 offset:1024
	ds_read_b128 v[198:201], v155 offset:2048
	s_add_i32 m0, s2, 0x18000
	s_nop 0
	global_load_lds_dwordx4 v134, s[28:29]
	ds_read_b128 v[202:205], v155 offset:3072
	ds_read_b128 v[206:209], v155 offset:4096
	ds_read_b128 v[210:213], v155 offset:5120
	s_add_i32 m0, s2, 0x1a000
	s_nop 0
	global_load_lds_dwordx4 v130, s[28:29]
	ds_read_b128 v[214:217], v155 offset:6144
	ds_read_b128 v[218:221], v155 offset:7168
	ds_read_b128 v[156:159], v153 offset:0
	s_add_u32 s30, s28, 0x20000
	s_addc_u32 s31, s29, 0
	s_add_i32 m0, s2, 0x19000
	s_nop 0
	global_load_lds_dwordx4 v134, s[30:31]
	ds_read_b128 v[160:163], v153 offset:1024
	ds_read_b128 v[164:167], v153 offset:2048
	ds_read_b128 v[168:171], v153 offset:3072
	s_add_i32 m0, s2, 0x1b000
	s_nop 0
	global_load_lds_dwordx4 v130, s[30:31]
	ds_read_b128 v[174:177], v153 offset:16384
	ds_read_b128 v[178:181], v153 offset:17408
	ds_read_b128 v[182:185], v153 offset:18432
	s_add_u32 s30, s28, 0x80000
	s_addc_u32 s31, s29, 0
	s_add_i32 m0, s2, 0x1c000
	s_nop 0
	global_load_lds_dwordx4 v134, s[30:31]
	ds_read_b128 v[186:189], v153 offset:19456
	ds_read_b128 v[222:225], v155 offset:16384
	ds_read_b128 v[226:229], v155 offset:17408
	s_add_i32 m0, s2, 0x1e000
	s_nop 0
	global_load_lds_dwordx4 v130, s[30:31]
	ds_read_b128 v[230:233], v155 offset:18432
	ds_read_b128 v[234:237], v155 offset:19456
	ds_read_b128 v[238:241], v155 offset:20480
	s_add_u32 s30, s28, 0xa0000
	s_addc_u32 s31, s29, 0
	s_add_i32 m0, s2, 0x1d000
	s_nop 0
	global_load_lds_dwordx4 v134, s[30:31]
	ds_read_b128 v[242:245], v155 offset:21504
	ds_read_b128 v[246:249], v155 offset:22528
	ds_read_b128 v[250:253], v155 offset:23552
	s_add_i32 m0, s2, 0x1f000
	s_nop 0
	global_load_lds_dwordx4 v130, s[30:31]
	s_add_u32 s28, s28, 0x80
	s_addc_u32 s29, s29, 0
	s_waitcnt vmcnt(8) lgkmcnt(0)
	s_barrier
	v_mfma_f32_16x16x32_bf16 v[126:129], v[156:159], v[190:193], v[126:129]
	v_mfma_f32_16x16x32_bf16 v[126:129], v[160:163], v[194:197], v[126:129]
	v_mfma_f32_16x16x32_bf16 v[122:125], v[168:171], v[194:197], v[122:125]
	v_mfma_f32_16x16x32_bf16 v[122:125], v[164:167], v[190:193], v[122:125]
	v_mfma_f32_16x16x32_bf16 v[118:121], v[174:177], v[190:193], v[118:121]
	v_mfma_f32_16x16x32_bf16 v[118:121], v[178:181], v[194:197], v[118:121]
	v_mfma_f32_16x16x32_bf16 v[114:117], v[186:189], v[194:197], v[114:117]
	v_mfma_f32_16x16x32_bf16 v[114:117], v[182:185], v[190:193], v[114:117]
	v_mfma_f32_16x16x32_bf16 v[98:101], v[182:185], v[198:201], v[98:101]
	v_mfma_f32_16x16x32_bf16 v[98:101], v[186:189], v[202:205], v[98:101]
	v_mfma_f32_16x16x32_bf16 v[102:105], v[178:181], v[202:205], v[102:105]
	v_mfma_f32_16x16x32_bf16 v[102:105], v[174:177], v[198:201], v[102:105]
	v_mfma_f32_16x16x32_bf16 v[106:109], v[164:167], v[198:201], v[106:109]
	v_mfma_f32_16x16x32_bf16 v[106:109], v[168:171], v[202:205], v[106:109]
	v_mfma_f32_16x16x32_bf16 v[110:113], v[160:163], v[202:205], v[110:113]
	v_mfma_f32_16x16x32_bf16 v[110:113], v[156:159], v[198:201], v[110:113]
	v_mfma_f32_16x16x32_bf16 v[94:97], v[156:159], v[206:209], v[94:97]
	v_mfma_f32_16x16x32_bf16 v[94:97], v[160:163], v[210:213], v[94:97]
	v_mfma_f32_16x16x32_bf16 v[90:93], v[168:171], v[210:213], v[90:93]
	v_mfma_f32_16x16x32_bf16 v[90:93], v[164:167], v[206:209], v[90:93]
	v_mfma_f32_16x16x32_bf16 v[86:89], v[174:177], v[206:209], v[86:89]
	v_mfma_f32_16x16x32_bf16 v[86:89], v[178:181], v[210:213], v[86:89]
	v_mfma_f32_16x16x32_bf16 v[82:85], v[186:189], v[210:213], v[82:85]
	v_mfma_f32_16x16x32_bf16 v[82:85], v[182:185], v[206:209], v[82:85]
	v_mfma_f32_16x16x32_bf16 v[66:69], v[182:185], v[214:217], v[66:69]
	v_mfma_f32_16x16x32_bf16 v[66:69], v[186:189], v[218:221], v[66:69]
	v_mfma_f32_16x16x32_bf16 v[70:73], v[178:181], v[218:221], v[70:73]
	v_mfma_f32_16x16x32_bf16 v[70:73], v[174:177], v[214:217], v[70:73]
	v_mfma_f32_16x16x32_bf16 v[74:77], v[164:167], v[214:217], v[74:77]
	v_mfma_f32_16x16x32_bf16 v[74:77], v[168:171], v[218:221], v[74:77]
	v_mfma_f32_16x16x32_bf16 v[78:81], v[160:163], v[218:221], v[78:81]
	v_mfma_f32_16x16x32_bf16 v[78:81], v[156:159], v[214:217], v[78:81]
	v_mfma_f32_16x16x32_bf16 v[62:65], v[156:159], v[222:225], v[62:65]
	v_mfma_f32_16x16x32_bf16 v[62:65], v[160:163], v[226:229], v[62:65]
	v_mfma_f32_16x16x32_bf16 v[58:61], v[168:171], v[226:229], v[58:61]
	v_mfma_f32_16x16x32_bf16 v[58:61], v[164:167], v[222:225], v[58:61]
	v_mfma_f32_16x16x32_bf16 v[54:57], v[174:177], v[222:225], v[54:57]
	v_mfma_f32_16x16x32_bf16 v[54:57], v[178:181], v[226:229], v[54:57]
	v_mfma_f32_16x16x32_bf16 v[50:53], v[186:189], v[226:229], v[50:53]
	v_mfma_f32_16x16x32_bf16 v[50:53], v[182:185], v[222:225], v[50:53]
	v_mfma_f32_16x16x32_bf16 v[34:37], v[182:185], v[230:233], v[34:37]
	v_mfma_f32_16x16x32_bf16 v[34:37], v[186:189], v[234:237], v[34:37]
	v_mfma_f32_16x16x32_bf16 v[38:41], v[178:181], v[234:237], v[38:41]
	v_mfma_f32_16x16x32_bf16 v[38:41], v[174:177], v[230:233], v[38:41]
	v_mfma_f32_16x16x32_bf16 v[42:45], v[164:167], v[230:233], v[42:45]
	v_mfma_f32_16x16x32_bf16 v[42:45], v[168:171], v[234:237], v[42:45]
	v_mfma_f32_16x16x32_bf16 v[46:49], v[160:163], v[234:237], v[46:49]
	v_mfma_f32_16x16x32_bf16 v[46:49], v[156:159], v[230:233], v[46:49]
	v_mfma_f32_16x16x32_bf16 v[30:33], v[156:159], v[238:241], v[30:33]
	v_mfma_f32_16x16x32_bf16 v[30:33], v[160:163], v[242:245], v[30:33]
	v_mfma_f32_16x16x32_bf16 v[26:29], v[168:171], v[242:245], v[26:29]
	v_mfma_f32_16x16x32_bf16 v[26:29], v[164:167], v[238:241], v[26:29]
	v_mfma_f32_16x16x32_bf16 v[22:25], v[174:177], v[238:241], v[22:25]
	v_mfma_f32_16x16x32_bf16 v[22:25], v[178:181], v[242:245], v[22:25]
	v_mfma_f32_16x16x32_bf16 v[18:21], v[186:189], v[242:245], v[18:21]
	v_mfma_f32_16x16x32_bf16 v[18:21], v[182:185], v[238:241], v[18:21]
	v_mfma_f32_16x16x32_bf16 v[2:5], v[182:185], v[246:249], v[2:5]
	v_mfma_f32_16x16x32_bf16 v[2:5], v[186:189], v[250:253], v[2:5]
	v_mfma_f32_16x16x32_bf16 v[6:9], v[178:181], v[250:253], v[6:9]
	v_mfma_f32_16x16x32_bf16 v[6:9], v[174:177], v[246:249], v[6:9]
	v_mfma_f32_16x16x32_bf16 v[10:13], v[164:167], v[246:249], v[10:13]
	v_mfma_f32_16x16x32_bf16 v[10:13], v[168:171], v[250:253], v[10:13]
	v_mfma_f32_16x16x32_bf16 v[14:17], v[160:163], v[250:253], v[14:17]
	v_mfma_f32_16x16x32_bf16 v[14:17], v[156:159], v[246:249], v[14:17]
	s_waitcnt vmcnt(0)
	s_barrier
; #define PG8_STAGE(bufoff, gbase, voff) do { _Pragma("unroll") for (int _i = 0; _i < 2; ++_i) \
;         __builtin_amdgcn_global_load_lds((const unsigned*)((const char*)(gbase) + (voff)[_i]), (PG8_LAS unsigned*)(lds + (bufoff) + ldsw + _i * 8192), 16, 0, 0); } while (0)
; #define PG8_LDA(dst, b, h) do { _Pragma("unroll") for (int m = 0; m < 4; ++m) _Pragma("unroll") for (int k = 0; k < 2; ++k) dst[m][k] = *(const PG8_LAS bf16x8*)(lds + PG8_SA(b, h) + aoff + m * 2048 + k * 1024); } while (0)
; #define PG8_LDB(dst, b, h) do { _Pragma("unroll") for (int n = 0; n < 2; ++n) _Pragma("unroll") for (int k = 0; k < 2; ++k) dst[n][k] = *(const PG8_LAS bf16x8*)(lds + PG8_SB(b, h) + boff + n * 2048 + k * 1024); } while (0)
; #define PG8_MMA(ai, bj, At, Bt) do { __builtin_amdgcn_s_setprio(1); _Pragma("unroll") for (int m = 0; m < 4; ++m) _Pragma("unroll") for (int n = 0; n < 2; ++n) _Pragma("unroll") for (int k = 0; k < 2; ++k) \
;         acc[ai][bj][m][n] = __builtin_amdgcn_mfma_f32_16x16x32_bf16(Bt[n][k], At[m][k], acc[ai][bj][m][n], 0, 0, 0); __builtin_amdgcn_s_setprio(0); } while (0)
; #define PG8_WAIT_V(n) asm volatile("s_waitcnt vmcnt(" #n ")" ::: "memory")
; #define PG8_WAIT_L(n) asm volatile("s_waitcnt lgkmcnt(" #n ")" ::: "memory")
; #define PG8_BAR __builtin_amdgcn_s_barrier()
; #define PG8_SCHED __builtin_amdgcn_sched_barrier(0)
; template <class Epi, class Sched, bool ALIGN_EPI>
; __device__ __forceinline__ void gemm_phase(PG8_LAS unsigned char* lds, const Gemm g, const Sched& S, const Epi& E) {
;     ...
;             PG8_LDB(B0, 1, 0); PG8_LDB(B1, 1, 1); PG8_SCHED; PG8_LDA(At, 1, 0); PG8_STAGE(PG8_SA(0, 1), a2 + hstepA, voffA);
;             PG8_WAIT_V(8); PG8_WAIT_L(0); PG8_BAR; PG8_MMA(0, 0, At, B0); PG8_MMA(0, 1, At, B1); PG8_BAR; PG8_SCHED;
;             PG8_LDA(At, 1, 1); PG8_STAGE(PG8_SB(1, 0), b3, voffB); PG8_STAGE(PG8_SB(1, 1), b3 + hstepB, voffB); PG8_STAGE(PG8_SA(1, 0), a3, voffA);
;             PG8_WAIT_V(8); PG8_WAIT_L(0); PG8_BAR; PG8_MMA(1, 0, At, B0); PG8_MMA(1, 1, At, B1); PG8_BAR; PG8_SCHED;
;         }
;         if constexpr (ALIGN_EPI) { if (wr == 0) PG8_BAR; }
;         E(acc, cur, wr, wc, fr, fq);
;         if (!has_next) break;
	ds_read_b128 v[190:193], v155 offset:32768
	ds_read_b128 v[194:197], v155 offset:33792
	ds_read_b128 v[198:201], v155 offset:34816
	s_cmp_eq_u32 s49, 15
	s_cselect_b32 s28, s50, s28
	s_cselect_b32 s29, s51, s29
	s_add_i32 m0, s2, 0x10000
	s_nop 0
	global_load_lds_dwordx4 v134, s[28:29]
	ds_read_b128 v[202:205], v155 offset:35840
	ds_read_b128 v[206:209], v155 offset:36864
	ds_read_b128 v[210:213], v155 offset:37888
	s_add_i32 m0, s2, 0x12000
	s_nop 0
	global_load_lds_dwordx4 v130, s[28:29]
	ds_read_b128 v[214:217], v155 offset:38912
	ds_read_b128 v[218:221], v155 offset:39936
	ds_read_b128 v[156:159], v153 offset:32768
	s_add_u32 s30, s28, 0x20000
	s_addc_u32 s31, s29, 0
	s_add_i32 m0, s2, 0x11000
	s_nop 0
	global_load_lds_dwordx4 v134, s[30:31]
	ds_read_b128 v[160:163], v153 offset:33792
	ds_read_b128 v[164:167], v153 offset:34816
	ds_read_b128 v[168:171], v153 offset:35840
	s_add_i32 m0, s2, 0x13000
	s_nop 0
	global_load_lds_dwordx4 v130, s[30:31]
	ds_read_b128 v[174:177], v153 offset:49152
	ds_read_b128 v[178:181], v153 offset:50176
	ds_read_b128 v[182:185], v153 offset:51200
	s_add_u32 s30, s28, 0x80000
	s_addc_u32 s31, s29, 0
	s_add_i32 m0, s2, 0x14000
	s_nop 0
	global_load_lds_dwordx4 v134, s[30:31]
	ds_read_b128 v[186:189], v153 offset:52224
	ds_read_b128 v[222:225], v155 offset:49152
	ds_read_b128 v[226:229], v155 offset:50176
	s_add_i32 m0, s2, 0x16000
	s_nop 0
	global_load_lds_dwordx4 v130, s[30:31]
	ds_read_b128 v[230:233], v155 offset:51200
	ds_read_b128 v[234:237], v155 offset:52224
	ds_read_b128 v[238:241], v155 offset:53248
	s_add_u32 s30, s28, 0xa0000
	s_addc_u32 s31, s29, 0
	s_add_i32 m0, s2, 0x15000
	s_nop 0
	global_load_lds_dwordx4 v134, s[30:31]
	ds_read_b128 v[242:245], v155 offset:54272
	ds_read_b128 v[246:249], v155 offset:55296
	ds_read_b128 v[250:253], v155 offset:56320
	s_add_i32 m0, s2, 0x17000
	s_nop 0
	global_load_lds_dwordx4 v130, s[30:31]
	s_add_u32 s28, s28, 0x80
	s_addc_u32 s29, s29, 0
	s_waitcnt vmcnt(8) lgkmcnt(0)
	s_barrier
	v_mfma_f32_16x16x32_bf16 v[126:129], v[156:159], v[190:193], v[126:129]
	v_mfma_f32_16x16x32_bf16 v[126:129], v[160:163], v[194:197], v[126:129]
	v_mfma_f32_16x16x32_bf16 v[122:125], v[168:171], v[194:197], v[122:125]
	v_mfma_f32_16x16x32_bf16 v[122:125], v[164:167], v[190:193], v[122:125]
	v_mfma_f32_16x16x32_bf16 v[118:121], v[174:177], v[190:193], v[118:121]
	v_mfma_f32_16x16x32_bf16 v[118:121], v[178:181], v[194:197], v[118:121]
	v_mfma_f32_16x16x32_bf16 v[114:117], v[186:189], v[194:197], v[114:117]
	v_mfma_f32_16x16x32_bf16 v[114:117], v[182:185], v[190:193], v[114:117]
	v_mfma_f32_16x16x32_bf16 v[98:101], v[182:185], v[198:201], v[98:101]
	v_mfma_f32_16x16x32_bf16 v[98:101], v[186:189], v[202:205], v[98:101]
	v_mfma_f32_16x16x32_bf16 v[102:105], v[178:181], v[202:205], v[102:105]
	v_mfma_f32_16x16x32_bf16 v[102:105], v[174:177], v[198:201], v[102:105]
	v_mfma_f32_16x16x32_bf16 v[106:109], v[164:167], v[198:201], v[106:109]
	v_mfma_f32_16x16x32_bf16 v[106:109], v[168:171], v[202:205], v[106:109]
	v_mfma_f32_16x16x32_bf16 v[110:113], v[160:163], v[202:205], v[110:113]
	v_mfma_f32_16x16x32_bf16 v[110:113], v[156:159], v[198:201], v[110:113]
	v_mfma_f32_16x16x32_bf16 v[94:97], v[156:159], v[206:209], v[94:97]
	v_mfma_f32_16x16x32_bf16 v[94:97], v[160:163], v[210:213], v[94:97]
	v_mfma_f32_16x16x32_bf16 v[90:93], v[168:171], v[210:213], v[90:93]
	v_mfma_f32_16x16x32_bf16 v[90:93], v[164:167], v[206:209], v[90:93]
	v_mfma_f32_16x16x32_bf16 v[86:89], v[174:177], v[206:209], v[86:89]
	v_mfma_f32_16x16x32_bf16 v[86:89], v[178:181], v[210:213], v[86:89]
	v_mfma_f32_16x16x32_bf16 v[82:85], v[186:189], v[210:213], v[82:85]
	v_mfma_f32_16x16x32_bf16 v[82:85], v[182:185], v[206:209], v[82:85]
	v_mfma_f32_16x16x32_bf16 v[66:69], v[182:185], v[214:217], v[66:69]
	v_mfma_f32_16x16x32_bf16 v[66:69], v[186:189], v[218:221], v[66:69]
	v_mfma_f32_16x16x32_bf16 v[70:73], v[178:181], v[218:221], v[70:73]
	v_mfma_f32_16x16x32_bf16 v[70:73], v[174:177], v[214:217], v[70:73]
	v_mfma_f32_16x16x32_bf16 v[74:77], v[164:167], v[214:217], v[74:77]
	v_mfma_f32_16x16x32_bf16 v[74:77], v[168:171], v[218:221], v[74:77]
	v_mfma_f32_16x16x32_bf16 v[78:81], v[160:163], v[218:221], v[78:81]
	v_mfma_f32_16x16x32_bf16 v[78:81], v[156:159], v[214:217], v[78:81]
	v_mfma_f32_16x16x32_bf16 v[62:65], v[156:159], v[222:225], v[62:65]
	v_mfma_f32_16x16x32_bf16 v[62:65], v[160:163], v[226:229], v[62:65]
	v_mfma_f32_16x16x32_bf16 v[58:61], v[168:171], v[226:229], v[58:61]
	v_mfma_f32_16x16x32_bf16 v[58:61], v[164:167], v[222:225], v[58:61]
	v_mfma_f32_16x16x32_bf16 v[54:57], v[174:177], v[222:225], v[54:57]
	v_mfma_f32_16x16x32_bf16 v[54:57], v[178:181], v[226:229], v[54:57]
	v_mfma_f32_16x16x32_bf16 v[50:53], v[186:189], v[226:229], v[50:53]
	v_mfma_f32_16x16x32_bf16 v[50:53], v[182:185], v[222:225], v[50:53]
	v_mfma_f32_16x16x32_bf16 v[34:37], v[182:185], v[230:233], v[34:37]
	v_mfma_f32_16x16x32_bf16 v[34:37], v[186:189], v[234:237], v[34:37]
	v_mfma_f32_16x16x32_bf16 v[38:41], v[178:181], v[234:237], v[38:41]
	v_mfma_f32_16x16x32_bf16 v[38:41], v[174:177], v[230:233], v[38:41]
	v_mfma_f32_16x16x32_bf16 v[42:45], v[164:167], v[230:233], v[42:45]
	v_mfma_f32_16x16x32_bf16 v[42:45], v[168:171], v[234:237], v[42:45]
	v_mfma_f32_16x16x32_bf16 v[46:49], v[160:163], v[234:237], v[46:49]
	v_mfma_f32_16x16x32_bf16 v[46:49], v[156:159], v[230:233], v[46:49]
	v_mfma_f32_16x16x32_bf16 v[30:33], v[156:159], v[238:241], v[30:33]
	v_mfma_f32_16x16x32_bf16 v[30:33], v[160:163], v[242:245], v[30:33]
	v_mfma_f32_16x16x32_bf16 v[26:29], v[168:171], v[242:245], v[26:29]
	v_mfma_f32_16x16x32_bf16 v[26:29], v[164:167], v[238:241], v[26:29]
	v_mfma_f32_16x16x32_bf16 v[22:25], v[174:177], v[238:241], v[22:25]
	v_mfma_f32_16x16x32_bf16 v[22:25], v[178:181], v[242:245], v[22:25]
	v_mfma_f32_16x16x32_bf16 v[18:21], v[186:189], v[242:245], v[18:21]
	v_mfma_f32_16x16x32_bf16 v[18:21], v[182:185], v[238:241], v[18:21]
	v_mfma_f32_16x16x32_bf16 v[2:5], v[182:185], v[246:249], v[2:5]
	v_mfma_f32_16x16x32_bf16 v[2:5], v[186:189], v[250:253], v[2:5]
	v_mfma_f32_16x16x32_bf16 v[6:9], v[178:181], v[250:253], v[6:9]
	v_mfma_f32_16x16x32_bf16 v[6:9], v[174:177], v[246:249], v[6:9]
	v_mfma_f32_16x16x32_bf16 v[10:13], v[164:167], v[246:249], v[10:13]
	v_mfma_f32_16x16x32_bf16 v[10:13], v[168:171], v[250:253], v[10:13]
	v_mfma_f32_16x16x32_bf16 v[14:17], v[160:163], v[250:253], v[14:17]
	v_mfma_f32_16x16x32_bf16 v[14:17], v[156:159], v[246:249], v[14:17]
	s_waitcnt vmcnt(0)
	s_barrier
	s_add_i32 s49, s49, 1
	s_cmp_lt_u32 s49, 16
	s_cbranch_scc1 .Lp8k_A_loop
	s_branch .Lp8k_done

; #define PG8_STAGE(bufoff, gbase, voff) do { _Pragma("unroll") for (int _i = 0; _i < 2; ++_i) \
;         __builtin_amdgcn_global_load_lds((const unsigned*)((const char*)(gbase) + (voff)[_i]), (PG8_LAS unsigned*)(lds + (bufoff) + ldsw + _i * 8192), 16, 0, 0); } while (0)
; #define PG8_LDA(dst, b, h) do { _Pragma("unroll") for (int m = 0; m < 4; ++m) _Pragma("unroll") for (int k = 0; k < 2; ++k) dst[m][k] = *(const PG8_LAS bf16x8*)(lds + PG8_SA(b, h) + aoff + m * 2048 + k * 1024); } while (0)
; #define PG8_LDB(dst, b, h) do { _Pragma("unroll") for (int n = 0; n < 2; ++n) _Pragma("unroll") for (int k = 0; k < 2; ++k) dst[n][k] = *(const PG8_LAS bf16x8*)(lds + PG8_SB(b, h) + boff + n * 2048 + k * 1024); } while (0)
; #define PG8_BAR __builtin_amdgcn_s_barrier()
; #define PG8_SCHED __builtin_amdgcn_sched_barrier(0)
; template <class Epi, class Sched, bool ALIGN_EPI>
; __device__ __forceinline__ void gemm_phase(PG8_LAS unsigned char* lds, const Gemm g, const Sched& S, const Epi& E) {
;     ...
;             const char* a2 = last ? nA : cA + (size_t)(t + 2) * kstepA; const char* b2 = last ? nB : cB + (size_t)(t + 2) * kstep;
;             const char* a3 = a2 + kstepA; const char* b3 = b2 + kstep;
;             PG8_LDB(B0, 0, 0); PG8_LDB(B1, 0, 1); PG8_SCHED; PG8_LDA(At, 0, 0); PG8_STAGE(PG8_SA(1, 1), a1 + hstepA, voffA);
;     ...
;         cur = nxt; cA = nA; cB = nB; ++ui;
;         if constexpr (ALIGN_EPI) { if (wr == 1) PG8_BAR; }
.LBB0_935:
	s_and_b64 vcc, exec, s[14:15]
	s_cbranch_vccz .Lhaft9_skip
	s_add_u32 s28, s24, 0x80
	s_addc_u32 s29, s25, 0
	ds_read_b128 v[194:197], v157 offset:0
	ds_read_b128 v[198:201], v157 offset:1024
	ds_read_b128 v[202:205], v157 offset:2048
	s_add_i32 m0, s60, 0x18000
	s_nop 0
	global_load_lds_dwordx4 v132, s[28:29]
	ds_read_b128 v[206:209], v157 offset:3072
	ds_read_b128 v[210:213], v157 offset:4096
	ds_read_b128 v[214:217], v157 offset:5120
	s_add_i32 m0, s60, 0x1a000
	s_nop 0
	global_load_lds_dwordx4 v136, s[28:29]
	ds_read_b128 v[218:221], v157 offset:6144
	ds_read_b128 v[222:225], v157 offset:7168
	ds_read_b128 v[158:161], v155 offset:0
	s_add_u32 s30, s28, 0x58000
	s_addc_u32 s31, s29, 0
	s_add_i32 m0, s60, 0x19000
	s_nop 0
	global_load_lds_dwordx4 v132, s[30:31]
	ds_read_b128 v[162:165], v155 offset:1024
	ds_read_b128 v[166:169], v155 offset:2048
	ds_read_b128 v[174:177], v155 offset:3072
	s_add_i32 m0, s60, 0x1b000
	s_nop 0
	global_load_lds_dwordx4 v136, s[30:31]
	ds_read_b128 v[178:181], v155 offset:16384
	ds_read_b128 v[182:185], v155 offset:17408
	ds_read_b128 v[186:189], v155 offset:18432
	s_add_u32 s30, s28, 0x160000
	s_addc_u32 s31, s29, 0
	s_add_i32 m0, s60, 0x1c000
	s_nop 0
	global_load_lds_dwordx4 v132, s[30:31]
	ds_read_b128 v[190:193], v155 offset:19456
	ds_read_b128 v[226:229], v157 offset:16384
	ds_read_b128 v[230:233], v157 offset:17408
	s_add_i32 m0, s60, 0x1e000
	s_nop 0
	global_load_lds_dwordx4 v136, s[30:31]
	ds_read_b128 v[234:237], v157 offset:18432
	ds_read_b128 v[238:241], v157 offset:19456
	ds_read_b128 v[242:245], v157 offset:20480
	s_add_u32 s30, s28, 0x1b8000
	s_addc_u32 s31, s29, 0
	s_add_i32 m0, s60, 0x1d000
	s_nop 0
	global_load_lds_dwordx4 v132, s[30:31]
	ds_read_b128 v[246:249], v157 offset:21504
	ds_read_b128 v[250:253], v157 offset:22528
	ds_read_b128 v[142:145], v157 offset:23552
	s_add_i32 m0, s60, 0x1f000
	s_nop 0
	global_load_lds_dwordx4 v136, s[30:31]
	s_add_u32 s28, s28, 0x80
	s_addc_u32 s29, s29, 0

; #define PG8_STAGE(bufoff, gbase, voff) do { _Pragma("unroll") for (int _i = 0; _i < 2; ++_i) \
;         __builtin_amdgcn_global_load_lds((const unsigned*)((const char*)(gbase) + (voff)[_i]), (PG8_LAS unsigned*)(lds + (bufoff) + ldsw + _i * 8192), 16, 0, 0); } while (0)
; #define PG8_LDA(dst, b, h) do { _Pragma("unroll") for (int m = 0; m < 4; ++m) _Pragma("unroll") for (int k = 0; k < 2; ++k) dst[m][k] = *(const PG8_LAS bf16x8*)(lds + PG8_SA(b, h) + aoff + m * 2048 + k * 1024); } while (0)
; #define PG8_LDB(dst, b, h) do { _Pragma("unroll") for (int n = 0; n < 2; ++n) _Pragma("unroll") for (int k = 0; k < 2; ++k) dst[n][k] = *(const PG8_LAS bf16x8*)(lds + PG8_SB(b, h) + boff + n * 2048 + k * 1024); } while (0)
; #define PG8_SCHED __builtin_amdgcn_sched_barrier(0)
; template <class Epi, class Sched, bool ALIGN_EPI>
; __device__ __forceinline__ void gemm_phase(PG8_LAS unsigned char* lds, const Gemm g, const Sched& S, const Epi& E) {
;     ...
;         const size_t tail_ = has_next ? 0 : tailoff; const char* nA = (has_next ? (const char*)g.A + (size_t)nxt.pm * tstepA : cA) + (has_next ? 0 : tailoffA); const char* nB = (has_next ? (const char*)g.Bt + (size_t)nxt.pn * tstepB : cB) + tail_;
;         for (int t = 0; t < nt; t += 2) {
;             if constexpr (Epi::MIDK) { if (t == (nt >> 1)) E.midk(acc, cur, wr, fr); }
;             const bool last = (t == nt - 2);
;             const char* a1 = cA + (size_t)(t + 1) * kstepA;
;             const char* a2 = last ? nA : cA + (size_t)(t + 2) * kstepA; const char* b2 = last ? nB : cB + (size_t)(t + 2) * kstep;
;             const char* a3 = a2 + kstepA; const char* b3 = b2 + kstep;
;             PG8_LDB(B0, 0, 0); PG8_LDB(B1, 0, 1); PG8_SCHED; PG8_LDA(At, 0, 0); PG8_STAGE(PG8_SA(1, 1), a1 + hstepA, voffA);
.Lh9_join:
	s_and_b32 s60, s37, 0xfff
	s_mov_b32 s57, 0
	s_cmp_lt_u32 s37, 0x1000
	s_cbranch_scc0 .Lp9k_B_init
	s_setprio 0
	s_mov_b64 s[58:59], s[24:25]
	s_cmp_eq_u32 s42, 1
	s_cbranch_scc1 .Lp9k_A_first
	s_add_u32 s28, s28, 0x100
	s_addc_u32 s29, s29, 0
	s_branch .Lp9k_A_entry
